# c15 + pass A unit end waits only for the L2 touches (vmcnt(32)), result stores stay in flight across the unit boundary
# baseline (speedup 1.0000x reference)
.LBB0_358:
	v_mul_lo_u32 v0, v99, s25
	v_lshl_add_u32 v143, v100, 2, v0
	v_add_u32_e32 v58, 0x8200, v143
	s_waitcnt lgkmcnt(0)
	s_barrier
	ds_read2_b32 v[60:61], v58 offset1:1
	v_add_u32_e32 v59, 0x8208, v143
	s_lshl_b64 s[2:3], s[26:27], 14
	v_readlane_b32 s4, v254, 45
	s_add_u32 s2, s4, s2
	s_waitcnt lgkmcnt(0)
	v_cvt_pk_bf16_f32 v58, v60, v61
	v_lshlrev_b32_e32 v62, 16, v58
	v_and_b32_e32 v63, 0xffff0000, v58
	v_pk_add_f32 v[60:61], v[60:61], v[62:63] neg_lo:[0,1] neg_hi:[0,1]
	v_readlane_b32 s4, v254, 47
	v_cvt_pk_bf16_f32 v66, v60, v61
	ds_read2_b32 v[60:61], v59 offset1:1
	s_addc_u32 s3, s4, s3
	s_lshl_b32 s4, s24, 2
	v_add3_u32 v0, v104, v103, s4
	v_add_u32_e32 v104, s4, v102
	s_waitcnt lgkmcnt(0)
	v_cvt_pk_bf16_f32 v59, v60, v61
	v_lshlrev_b32_e32 v62, 16, v59
	v_and_b32_e32 v63, 0xffff0000, v59
	v_pk_add_f32 v[60:61], v[60:61], v[62:63] neg_lo:[0,1] neg_hi:[0,1]
	v_add_u32_e32 v144, 0x1c700, v0
	v_cvt_pk_bf16_f32 v67, v60, v61
	v_add_u32_e32 v60, 0x8210, v143
	ds_read2_b32 v[62:63], v60 offset1:1
	v_add_u32_e32 v61, 0x8218, v143
	v_cmp_eq_u32_e32 vcc, v124, v120
	s_waitcnt lgkmcnt(0)
	v_cvt_pk_bf16_f32 v60, v62, v63
	v_lshlrev_b32_e32 v64, 16, v60
	v_and_b32_e32 v65, 0xffff0000, v60
	v_pk_add_f32 v[62:63], v[62:63], v[64:65] neg_lo:[0,1] neg_hi:[0,1]
	s_nop 0
	v_cvt_pk_bf16_f32 v68, v62, v63
	ds_read2_b32 v[62:63], v61 offset1:1
	ds_read2_b32 v[80:81], v104 offset1:16
	ds_read2_b32 v[78:79], v104 offset0:65 offset1:81
	ds_read2_b32 v[84:85], v104 offset0:130 offset1:146
	ds_read2_b32 v[82:83], v104 offset0:195 offset1:211
	s_waitcnt lgkmcnt(4)
	v_cvt_pk_bf16_f32 v61, v62, v63
	v_lshlrev_b32_e32 v64, 16, v61
	v_and_b32_e32 v65, 0xffff0000, v61
	v_pk_add_f32 v[62:63], v[62:63], v[64:65] neg_lo:[0,1] neg_hi:[0,1]
	s_waitcnt lgkmcnt(3)
	v_mov_b32_e32 v64, v80
	v_cvt_pk_bf16_f32 v69, v62, v63
	s_waitcnt lgkmcnt(2)
	v_cvt_pk_bf16_f32 v62, v80, v78
	v_mov_b32_e32 v65, v78
	v_lshlrev_b32_e32 v70, 16, v62
	v_and_b32_e32 v71, 0xffff0000, v62
	v_pk_add_f32 v[64:65], v[64:65], v[70:71] neg_lo:[0,1] neg_hi:[0,1]
	s_waitcnt lgkmcnt(0)
	v_cvt_pk_bf16_f32 v63, v84, v82
	v_cvt_pk_bf16_f32 v70, v64, v65
	v_mov_b32_e32 v64, v84
	v_mov_b32_e32 v65, v82
	v_lshlrev_b32_e32 v72, 16, v63
	v_and_b32_e32 v73, 0xffff0000, v63
	v_pk_add_f32 v[64:65], v[64:65], v[72:73] neg_lo:[0,1] neg_hi:[0,1]
	v_add_u32_e32 v78, 0x400, v144
	v_cvt_pk_bf16_f32 v71, v64, v65
	v_add_u32_e32 v65, 0x400, v104
	ds_read2_b32 v[88:89], v65 offset0:4 offset1:20
	ds_read2_b32 v[86:87], v65 offset0:69 offset1:85
	ds_read2_b32 v[98:99], v65 offset0:134 offset1:150
	ds_read2_b32 v[96:97], v65 offset0:199 offset1:215
	ds_read2_b32 v[110:111], v144 offset1:16
	ds_read2_b32 v[146:147], v144 offset0:65 offset1:81
	ds_read2_b32 v[148:149], v144 offset0:130 offset1:146
	ds_read2_b32 v[150:151], v144 offset0:195 offset1:211
	s_waitcnt lgkmcnt(7)
	v_mov_b32_e32 v72, v88
	s_waitcnt lgkmcnt(6)
	v_cvt_pk_bf16_f32 v64, v88, v86
	v_mov_b32_e32 v73, v86
	v_lshlrev_b32_e32 v74, 16, v64
	v_and_b32_e32 v75, 0xffff0000, v64
	s_waitcnt lgkmcnt(4)
	v_cvt_pk_bf16_f32 v65, v98, v96
	v_pk_add_f32 v[72:73], v[72:73], v[74:75] neg_lo:[0,1] neg_hi:[0,1]
	v_mov_b32_e32 v74, v98
	v_mov_b32_e32 v75, v96
	v_lshlrev_b32_e32 v76, 16, v65
	v_and_b32_e32 v77, 0xffff0000, v65
	ds_read2_b32 v[152:153], v78 offset0:4 offset1:20
	ds_read2_b32 v[154:155], v78 offset0:69 offset1:85
	v_pk_add_f32 v[74:75], v[74:75], v[76:77] neg_lo:[0,1] neg_hi:[0,1]
	s_waitcnt lgkmcnt(4)
	v_cvt_pk_bf16_f32 v100, v110, v146
	v_cvt_pk_bf16_f32 v72, v72, v73
	v_cvt_pk_bf16_f32 v73, v74, v75
	v_mov_b32_e32 v74, v110
	v_mov_b32_e32 v75, v146
	v_lshlrev_b32_e32 v76, 16, v100
	v_and_b32_e32 v77, 0xffff0000, v100
	ds_read2_b32 v[156:157], v78 offset0:134 offset1:150
	ds_read2_b32 v[158:159], v78 offset0:199 offset1:215
	v_pk_add_f32 v[74:75], v[74:75], v[76:77] neg_lo:[0,1] neg_hi:[0,1]
	s_waitcnt lgkmcnt(4)
	v_cvt_pk_bf16_f32 v101, v148, v150
	v_cvt_pk_bf16_f32 v106, v74, v75
	v_mov_b32_e32 v74, v148
	v_mov_b32_e32 v75, v150
	v_lshlrev_b32_e32 v76, 16, v101
	v_and_b32_e32 v77, 0xffff0000, v101
	v_pk_add_f32 v[74:75], v[74:75], v[76:77] neg_lo:[0,1] neg_hi:[0,1]
	s_waitcnt lgkmcnt(2)
	v_cvt_pk_bf16_f32 v102, v152, v154
	v_cvt_pk_bf16_f32 v107, v74, v75
	v_mov_b32_e32 v74, v152
	v_mov_b32_e32 v75, v154
	v_lshlrev_b32_e32 v76, 16, v102
	v_and_b32_e32 v77, 0xffff0000, v102
	v_pk_add_f32 v[74:75], v[74:75], v[76:77] neg_lo:[0,1] neg_hi:[0,1]
	s_waitcnt lgkmcnt(0)
	v_cvt_pk_bf16_f32 v103, v156, v158
	v_cvt_pk_bf16_f32 v108, v74, v75
	v_mov_b32_e32 v74, v156
	v_mov_b32_e32 v75, v158
	v_lshlrev_b32_e32 v76, 16, v103
	v_and_b32_e32 v77, 0xffff0000, v103
	v_pk_add_f32 v[74:75], v[74:75], v[76:77] neg_lo:[0,1] neg_hi:[0,1]
	v_mov_b32_e32 v78, v81
	v_cvt_pk_bf16_f32 v109, v74, v75
	v_mfma_f32_16x16x32_bf16 v[74:77], v[66:69], v[62:65], 0
	v_mov_b32_e32 v82, v85
	v_mov_b32_e32 v86, v89
	v_mov_b32_e32 v96, v99
	v_mfma_f32_16x16x32_bf16 v[70:73], v[58:61], v[70:73], v[74:77]
	v_mov_b32_e32 v146, v111
	v_mov_b32_e32 v150, v149
	v_mov_b32_e32 v154, v153
	v_mfma_f32_16x16x32_bf16 v[74:77], v[58:61], v[62:65], v[70:73]
	v_mov_b32_e32 v158, v157
	s_nop 2
	v_cvt_pk_bf16_f32 v70, v81, v79
	v_lshlrev_b32_e32 v72, 16, v70
	v_and_b32_e32 v73, 0xffff0000, v70
	v_pk_add_f32 v[72:73], v[78:79], v[72:73] neg_lo:[0,1] neg_hi:[0,1]
	v_cvt_pk_bf16_f32 v71, v85, v83
	v_cvt_pk_bf16_f32 v78, v72, v73
	v_lshlrev_b32_e32 v72, 16, v71
	v_and_b32_e32 v73, 0xffff0000, v71
	v_pk_add_f32 v[72:73], v[82:83], v[72:73] neg_lo:[0,1] neg_hi:[0,1]
	v_mfma_f32_16x16x32_bf16 v[62:65], v[66:69], v[100:103], 0
	v_cvt_pk_bf16_f32 v79, v72, v73
	v_cvt_pk_bf16_f32 v72, v89, v87
	v_cvt_pk_bf16_f32 v73, v99, v97
	v_lshlrev_b32_e32 v80, 16, v72
	v_and_b32_e32 v81, 0xffff0000, v72
	v_lshlrev_b32_e32 v82, 16, v73
	v_and_b32_e32 v83, 0xffff0000, v73
	v_pk_add_f32 v[80:81], v[86:87], v[80:81] neg_lo:[0,1] neg_hi:[0,1]
	v_pk_add_f32 v[82:83], v[96:97], v[82:83] neg_lo:[0,1] neg_hi:[0,1]
	v_cvt_pk_bf16_f32 v80, v80, v81
	v_cvt_pk_bf16_f32 v81, v82, v83
	v_cvt_pk_bf16_f32 v82, v111, v147
	v_lshlrev_b32_e32 v84, 16, v82
	v_and_b32_e32 v85, 0xffff0000, v82
	v_pk_add_f32 v[84:85], v[146:147], v[84:85] neg_lo:[0,1] neg_hi:[0,1]
	v_cvt_pk_bf16_f32 v83, v149, v151
	v_cvt_pk_bf16_f32 v86, v84, v85
	v_lshlrev_b32_e32 v84, 16, v83
	v_and_b32_e32 v85, 0xffff0000, v83
	v_pk_add_f32 v[84:85], v[150:151], v[84:85] neg_lo:[0,1] neg_hi:[0,1]
	v_mfma_f32_16x16x32_bf16 v[62:65], v[58:61], v[106:109], v[62:65]
	v_cvt_pk_bf16_f32 v87, v84, v85
	v_cvt_pk_bf16_f32 v84, v153, v155
	v_cvt_pk_bf16_f32 v85, v157, v159
	v_lshlrev_b32_e32 v88, 16, v84
	v_and_b32_e32 v89, 0xffff0000, v84
	v_lshlrev_b32_e32 v96, 16, v85
	v_and_b32_e32 v97, 0xffff0000, v85
	v_pk_add_f32 v[88:89], v[154:155], v[88:89] neg_lo:[0,1] neg_hi:[0,1]
	v_pk_add_f32 v[96:97], v[158:159], v[96:97] neg_lo:[0,1] neg_hi:[0,1]
	v_cvt_pk_bf16_f32 v88, v88, v89
	v_cvt_pk_bf16_f32 v89, v96, v97
	v_mfma_f32_16x16x32_bf16 v[96:99], v[66:69], v[70:73], 0
	v_mfma_f32_16x16x32_bf16 v[66:69], v[66:69], v[82:85], 0
	v_mfma_f32_16x16x32_bf16 v[78:81], v[58:61], v[78:81], v[96:99]
	v_mfma_f32_16x16x32_bf16 v[66:69], v[58:61], v[86:89], v[66:69]
	v_mfma_f32_16x16x32_bf16 v[62:65], v[58:61], v[100:103], v[62:65]
	v_mfma_f32_16x16x32_bf16 v[78:81], v[58:61], v[70:73], v[78:81]
	v_mfma_f32_16x16x32_bf16 v[66:69], v[58:61], v[82:85], v[66:69]
	v_add_u32_e32 v58, 0x8280, v143
	ds_read2_b32 v[60:61], v58 offset1:1
	v_add_u32_e32 v59, 0x8288, v143
	s_waitcnt lgkmcnt(0)
	v_cvt_pk_bf16_f32 v58, v60, v61
	v_lshlrev_b32_e32 v70, 16, v58
	v_and_b32_e32 v71, 0xffff0000, v58
	v_pk_add_f32 v[60:61], v[60:61], v[70:71] neg_lo:[0,1] neg_hi:[0,1]
	s_nop 0
	v_cvt_pk_bf16_f32 v70, v60, v61
	ds_read2_b32 v[60:61], v59 offset1:1
	s_waitcnt lgkmcnt(0)
	v_cvt_pk_bf16_f32 v59, v60, v61
	v_lshlrev_b32_e32 v72, 16, v59
	v_and_b32_e32 v73, 0xffff0000, v59
	v_pk_add_f32 v[60:61], v[60:61], v[72:73] neg_lo:[0,1] neg_hi:[0,1]
	s_nop 0
	v_cvt_pk_bf16_f32 v71, v60, v61
	v_add_u32_e32 v60, 0x8290, v143
	ds_read2_b32 v[72:73], v60 offset1:1
	v_add_u32_e32 v61, 0x8298, v143
	s_waitcnt lgkmcnt(0)
	v_cvt_pk_bf16_f32 v60, v72, v73
	v_lshlrev_b32_e32 v82, 16, v60
	v_and_b32_e32 v83, 0xffff0000, v60
	v_pk_add_f32 v[72:73], v[72:73], v[82:83] neg_lo:[0,1] neg_hi:[0,1]
	ds_read2_b32 v[82:83], v61 offset1:1
	v_cvt_pk_bf16_f32 v72, v72, v73
	s_waitcnt lgkmcnt(0)
	v_cvt_pk_bf16_f32 v61, v82, v83
	v_lshlrev_b32_e32 v84, 16, v61
	v_and_b32_e32 v85, 0xffff0000, v61
	v_pk_add_f32 v[82:83], v[82:83], v[84:85] neg_lo:[0,1] neg_hi:[0,1]
	s_nop 0
	v_cvt_pk_bf16_f32 v73, v82, v83
	v_add_u32_e32 v83, 0x2000, v104
	ds_read2_b32 v[98:99], v83 offset0:32 offset1:48
	ds_read2_b32 v[96:97], v83 offset0:97 offset1:113
	ds_read2_b32 v[102:103], v83 offset0:162 offset1:178
	ds_read2_b32 v[100:101], v83 offset0:227 offset1:243
	s_waitcnt lgkmcnt(3)
	v_mov_b32_e32 v84, v98
	s_waitcnt lgkmcnt(2)
	v_cvt_pk_bf16_f32 v82, v98, v96
	v_mov_b32_e32 v85, v96
	v_lshlrev_b32_e32 v86, 16, v82
	v_and_b32_e32 v87, 0xffff0000, v82
	v_pk_add_f32 v[84:85], v[84:85], v[86:87] neg_lo:[0,1] neg_hi:[0,1]
	s_waitcnt lgkmcnt(0)
	v_cvt_pk_bf16_f32 v83, v102, v100
	v_cvt_pk_bf16_f32 v86, v84, v85
	v_mov_b32_e32 v84, v102
	v_mov_b32_e32 v85, v100
	v_lshlrev_b32_e32 v88, 16, v83
	v_and_b32_e32 v89, 0xffff0000, v83
	v_pk_add_f32 v[84:85], v[84:85], v[88:89] neg_lo:[0,1] neg_hi:[0,1]
	v_add_u32_e32 v96, 0x2000, v144
	v_cvt_pk_bf16_f32 v87, v84, v85
	v_add_u32_e32 v85, 0x2400, v104
	ds_read2_b32 v[106:107], v85 offset0:36 offset1:52
	ds_read2_b32 v[104:105], v85 offset0:101 offset1:117
	v_mov_b32_e32 v100, v103
	s_waitcnt lgkmcnt(1)
	v_mov_b32_e32 v88, v106
	s_waitcnt lgkmcnt(0)
	v_cvt_pk_bf16_f32 v84, v106, v104
	v_mov_b32_e32 v89, v104
	v_lshlrev_b32_e32 v108, 16, v84
	v_and_b32_e32 v109, 0xffff0000, v84
	v_pk_add_f32 v[88:89], v[88:89], v[108:109] neg_lo:[0,1] neg_hi:[0,1]
	ds_read2_b32 v[110:111], v85 offset0:166 offset1:182
	ds_read2_b32 v[108:109], v85 offset0:231 offset1:247
	ds_read2_b32 v[154:155], v96 offset0:32 offset1:48
	ds_read2_b32 v[156:157], v96 offset0:97 offset1:113
	ds_read2_b32 v[158:159], v96 offset0:162 offset1:178
	ds_read2_b32 v[160:161], v96 offset0:227 offset1:243
	v_add_u32_e32 v96, 0x2400, v144
	s_waitcnt lgkmcnt(5)
	v_mov_b32_e32 v146, v110
	s_waitcnt lgkmcnt(4)
	v_cvt_pk_bf16_f32 v85, v110, v108
	v_mov_b32_e32 v147, v108
	v_lshlrev_b32_e32 v148, 16, v85
	v_and_b32_e32 v149, 0xffff0000, v85
	v_mfma_f32_16x16x32_bf16 v[74:77], v[70:73], v[82:85], v[74:77]
	v_add_f32_e64 v146, v146, -v148
	v_add_f32_e64 v147, v147, -v149
	v_cvt_pk_bf16_f32 v88, v88, v89
	v_cvt_pk_bf16_f32 v89, v146, v147
	s_waitcnt lgkmcnt(2)
	v_cvt_pk_bf16_f32 v146, v154, v156
	ds_read2_b32 v[144:145], v96 offset0:36 offset1:52
	ds_read2_b32 v[162:163], v96 offset0:101 offset1:117
	v_mov_b32_e32 v148, v154
	v_mov_b32_e32 v149, v156
	v_lshlrev_b32_e32 v150, 16, v146
	v_and_b32_e32 v151, 0xffff0000, v146
	v_pk_add_f32 v[148:149], v[148:149], v[150:151] neg_lo:[0,1] neg_hi:[0,1]
	s_waitcnt lgkmcnt(2)
	v_cvt_pk_bf16_f32 v147, v158, v160
	v_mfma_f32_16x16x32_bf16 v[74:77], v[58:61], v[86:89], v[74:77]
	v_cvt_pk_bf16_f32 v150, v148, v149
	v_mov_b32_e32 v148, v158
	v_mov_b32_e32 v149, v160
	v_lshlrev_b32_e32 v152, 16, v147
	v_and_b32_e32 v153, 0xffff0000, v147
	v_pk_add_f32 v[148:149], v[148:149], v[152:153] neg_lo:[0,1] neg_hi:[0,1]
	s_waitcnt lgkmcnt(1)
	v_mov_b32_e32 v152, v144
	v_cvt_pk_bf16_f32 v151, v148, v149
	s_waitcnt lgkmcnt(0)
	v_cvt_pk_bf16_f32 v148, v144, v162
	v_mov_b32_e32 v153, v162
	v_lshlrev_b32_e32 v164, 16, v148
	v_and_b32_e32 v165, 0xffff0000, v148
	v_mfma_f32_16x16x32_bf16 v[74:77], v[58:61], v[82:85], v[74:77]
	v_cvt_pk_bf16_f32 v82, v99, v97
	v_pk_add_f32 v[152:153], v[152:153], v[164:165] neg_lo:[0,1] neg_hi:[0,1]
	ds_read2_b32 v[164:165], v96 offset0:166 offset1:182
	ds_read2_b32 v[166:167], v96 offset0:231 offset1:247
	v_mov_b32_e32 v96, v99
	v_lshlrev_b32_e32 v84, 16, v82
	v_and_b32_e32 v85, 0xffff0000, v82
	v_pk_add_f32 v[84:85], v[96:97], v[84:85] neg_lo:[0,1] neg_hi:[0,1]
	v_cvt_pk_bf16_f32 v83, v103, v101
	v_cvt_pk_bf16_f32 v86, v84, v85
	v_lshlrev_b32_e32 v84, 16, v83
	v_and_b32_e32 v85, 0xffff0000, v83
	v_pk_add_f32 v[84:85], v[100:101], v[84:85] neg_lo:[0,1] neg_hi:[0,1]
	v_mov_b32_e32 v104, v107
	v_cvt_pk_bf16_f32 v87, v84, v85
	v_cvt_pk_bf16_f32 v84, v107, v105
	v_cvt_pk_bf16_f32 v85, v111, v109
	v_lshlrev_b32_e32 v88, 16, v84
	v_and_b32_e32 v89, 0xffff0000, v84
	v_mov_b32_e32 v108, v111
	v_lshlrev_b32_e32 v96, 16, v85
	v_and_b32_e32 v97, 0xffff0000, v85
	v_pk_add_f32 v[88:89], v[104:105], v[88:89] neg_lo:[0,1] neg_hi:[0,1]
	v_pk_add_f32 v[96:97], v[108:109], v[96:97] neg_lo:[0,1] neg_hi:[0,1]
	v_cvt_pk_bf16_f32 v88, v88, v89
	v_cvt_pk_bf16_f32 v89, v96, v97
	v_cvt_pk_bf16_f32 v96, v155, v157
	v_mov_b32_e32 v156, v155
	v_lshlrev_b32_e32 v98, 16, v96
	v_and_b32_e32 v99, 0xffff0000, v96
	v_pk_add_f32 v[98:99], v[156:157], v[98:99] neg_lo:[0,1] neg_hi:[0,1]
	v_cvt_pk_bf16_f32 v97, v159, v161
	v_cvt_pk_bf16_f32 v100, v98, v99
	v_mov_b32_e32 v160, v159
	v_lshlrev_b32_e32 v98, 16, v97
	v_and_b32_e32 v99, 0xffff0000, v97
	v_pk_add_f32 v[98:99], v[160:161], v[98:99] neg_lo:[0,1] neg_hi:[0,1]
	v_mfma_f32_16x16x32_bf16 v[78:81], v[70:73], v[82:85], v[78:81]
	s_waitcnt lgkmcnt(0)
	v_cvt_pk_bf16_f32 v149, v164, v166
	v_cvt_pk_bf16_f32 v101, v98, v99
	v_cvt_pk_bf16_f32 v98, v145, v163
	v_cvt_pk_bf16_f32 v99, v165, v167
	v_mfma_f32_16x16x32_bf16 v[62:65], v[70:73], v[146:149], v[62:65]
	v_mov_b32_e32 v168, v164
	v_mov_b32_e32 v169, v166
	v_lshlrev_b32_e32 v170, 16, v149
	v_mfma_f32_16x16x32_bf16 v[66:69], v[70:73], v[96:99], v[66:69]
	v_and_b32_e32 v171, 0xffff0000, v149
	v_mov_b32_e32 v162, v145
	v_lshlrev_b32_e32 v102, 16, v98
	v_and_b32_e32 v103, 0xffff0000, v98
	v_mov_b32_e32 v166, v165
	v_lshlrev_b32_e32 v104, 16, v99
	v_and_b32_e32 v105, 0xffff0000, v99
	v_pk_add_f32 v[168:169], v[168:169], v[170:171] neg_lo:[0,1] neg_hi:[0,1]
	v_pk_add_f32 v[102:103], v[162:163], v[102:103] neg_lo:[0,1] neg_hi:[0,1]
	v_pk_add_f32 v[104:105], v[166:167], v[104:105] neg_lo:[0,1] neg_hi:[0,1]
	v_mfma_f32_16x16x32_bf16 v[78:81], v[58:61], v[86:89], v[78:81]
	v_cvt_pk_bf16_f32 v152, v152, v153
	v_cvt_pk_bf16_f32 v153, v168, v169
	v_cvt_pk_bf16_f32 v102, v102, v103
	v_cvt_pk_bf16_f32 v103, v104, v105
	v_mfma_f32_16x16x32_bf16 v[62:65], v[58:61], v[150:153], v[62:65]
	ds_write_b32 v137, v74
	v_add_u32_e32 v106, 0x18600, v143
	v_add_u32_e32 v107, 0x20800, v0
	v_mfma_f32_16x16x32_bf16 v[66:69], v[58:61], v[100:103], v[66:69]
	v_add_u32_e32 v0, 0x14500, v0
	v_mfma_f32_16x16x32_bf16 v[78:81], v[58:61], v[82:85], v[78:81]
	v_mfma_f32_16x16x32_bf16 v[62:65], v[58:61], v[146:149], v[62:65]
	v_mfma_f32_16x16x32_bf16 v[58:61], v[58:61], v[96:99], v[66:69]
	s_nop 3
	v_lshl_add_u32 v66, v127, 2, v118
	ds_write_b32 v66, v75
	ds_write_b32 v138, v76
	ds_write_b32 v139, v77
	ds_write_b32 v140, v78
	v_lshl_add_u32 v66, v128, 2, v118
	ds_write_b32 v66, v79
	ds_write_b32 v141, v80
	ds_write_b32 v142, v81
	ds_write_b32 v129, v62
	ds_write_b32 v130, v63
	ds_write_b32 v131, v64
	ds_write_b32 v132, v65
	ds_write_b32 v133, v58
	ds_write_b32 v134, v59
	ds_write_b32 v135, v60
	ds_write_b32 v136, v61
	v_add_u32_e32 v58, 0x4000, v126
	s_waitcnt lgkmcnt(0)
	s_barrier
	ds_read2_b32 v[60:61], v58 offset0:64 offset1:129
	v_add_u32_e32 v59, 0x4200, v126
	v_add_u32_e32 v68, 0x400, v107
	s_waitcnt lgkmcnt(0)
	v_cvt_pk_bf16_f32 v58, v60, v61
	v_lshlrev_b32_e32 v62, 16, v58
	v_and_b32_e32 v63, 0xffff0000, v58
	v_pk_add_f32 v[60:61], v[60:61], v[62:63] neg_lo:[0,1] neg_hi:[0,1]
	s_nop 0
	v_cvt_pk_bf16_f32 v74, v60, v61
	ds_read2_b32 v[60:61], v59 offset0:66 offset1:131
	s_waitcnt lgkmcnt(0)
	v_cvt_pk_bf16_f32 v59, v60, v61
	v_lshlrev_b32_e32 v62, 16, v59
	v_and_b32_e32 v63, 0xffff0000, v59
	v_pk_add_f32 v[60:61], v[60:61], v[62:63] neg_lo:[0,1] neg_hi:[0,1]
	s_nop 0
	v_cvt_pk_bf16_f32 v75, v60, v61
	v_add_u32_e32 v60, 0x4400, v126
	ds_read2_b32 v[62:63], v60 offset0:68 offset1:133
	v_add_u32_e32 v61, 0x4600, v126
	s_waitcnt lgkmcnt(0)
	v_cvt_pk_bf16_f32 v60, v62, v63
	v_lshlrev_b32_e32 v64, 16, v60
	v_and_b32_e32 v65, 0xffff0000, v60
	v_pk_add_f32 v[62:63], v[62:63], v[64:65] neg_lo:[0,1] neg_hi:[0,1]
	s_nop 0
	v_cvt_pk_bf16_f32 v76, v62, v63
	ds_read2_b32 v[62:63], v61 offset0:70 offset1:135
	s_waitcnt lgkmcnt(0)
	v_cvt_pk_bf16_f32 v61, v62, v63
	v_lshlrev_b32_e32 v64, 16, v61
	v_and_b32_e32 v65, 0xffff0000, v61
	v_pk_add_f32 v[62:63], v[62:63], v[64:65] neg_lo:[0,1] neg_hi:[0,1]
	s_nop 0
	v_cvt_pk_bf16_f32 v77, v62, v63
	ds_read2_b32 v[62:63], v106 offset1:1
	s_waitcnt lgkmcnt(0)
	v_cvt_pk_bf16_f32 v78, v62, v63
	ds_read2_b32 v[62:63], v106 offset0:2 offset1:3
	s_waitcnt lgkmcnt(0)
	v_cvt_pk_bf16_f32 v79, v62, v63
	ds_read2_b32 v[62:63], v106 offset0:4 offset1:5
	s_waitcnt lgkmcnt(0)
	v_cvt_pk_bf16_f32 v80, v62, v63
	ds_read2_b32 v[62:63], v106 offset0:6 offset1:7
	ds_read2_b32 v[84:85], v107 offset1:16
	ds_read2_b32 v[82:83], v107 offset0:65 offset1:81
	ds_read2_b32 v[88:89], v107 offset0:130 offset1:146
	ds_read2_b32 v[86:87], v107 offset0:195 offset1:211
	ds_read2_b32 v[98:99], v68 offset0:4 offset1:20
	ds_read2_b32 v[96:97], v68 offset0:69 offset1:85
	ds_read2_b32 v[102:103], v68 offset0:134 offset1:150
	ds_read2_b32 v[100:101], v68 offset0:199 offset1:215
	s_waitcnt lgkmcnt(8)
	v_cvt_pk_bf16_f32 v81, v62, v63
	s_waitcnt lgkmcnt(6)
	v_cvt_pk_bf16_f32 v70, v84, v82
	v_mov_b32_e32 v62, v84
	v_mov_b32_e32 v63, v82
	v_lshlrev_b32_e32 v64, 16, v70
	v_and_b32_e32 v65, 0xffff0000, v70
	s_waitcnt lgkmcnt(4)
	v_cvt_pk_bf16_f32 v71, v88, v86
	ds_read2_b32 v[132:133], v0 offset1:16
	ds_read2_b32 v[104:105], v0 offset0:65 offset1:81
	v_pk_add_f32 v[62:63], v[62:63], v[64:65] neg_lo:[0,1] neg_hi:[0,1]
	v_mov_b32_e32 v64, v88
	v_mov_b32_e32 v65, v86
	v_lshlrev_b32_e32 v66, 16, v71
	v_and_b32_e32 v67, 0xffff0000, v71
	ds_read2_b32 v[134:135], v0 offset0:130 offset1:146
	ds_read2_b32 v[136:137], v0 offset0:195 offset1:211
	v_pk_add_f32 v[64:65], v[64:65], v[66:67] neg_lo:[0,1] neg_hi:[0,1]
	s_waitcnt lgkmcnt(6)
	v_cvt_pk_bf16_f32 v72, v98, v96
	v_add_u32_e32 v82, 0x400, v0
	v_cvt_pk_bf16_f32 v62, v62, v63
	v_cvt_pk_bf16_f32 v63, v64, v65
	v_mov_b32_e32 v64, v98
	v_mov_b32_e32 v65, v96
	v_lshlrev_b32_e32 v66, 16, v72
	v_and_b32_e32 v67, 0xffff0000, v72
	s_waitcnt lgkmcnt(4)
	v_cvt_pk_bf16_f32 v73, v102, v100
	ds_read2_b32 v[138:139], v82 offset0:4 offset1:20
	ds_read2_b32 v[140:141], v82 offset0:69 offset1:85
	v_pk_add_f32 v[64:65], v[64:65], v[66:67] neg_lo:[0,1] neg_hi:[0,1]
	v_mov_b32_e32 v66, v102
	v_mov_b32_e32 v67, v100
	v_lshlrev_b32_e32 v68, 16, v73
	v_and_b32_e32 v69, 0xffff0000, v73
	ds_read2_b32 v[142:143], v82 offset0:134 offset1:150
	ds_read2_b32 v[144:145], v82 offset0:199 offset1:215
	v_pk_add_f32 v[66:67], v[66:67], v[68:69] neg_lo:[0,1] neg_hi:[0,1]
	s_waitcnt lgkmcnt(6)
	v_cvt_pk_bf16_f32 v108, v132, v104
	v_cvt_pk_bf16_f32 v64, v64, v65
	v_cvt_pk_bf16_f32 v65, v66, v67
	v_mov_b32_e32 v66, v132
	v_mov_b32_e32 v67, v104
	v_lshlrev_b32_e32 v68, 16, v108
	v_and_b32_e32 v69, 0xffff0000, v108
	s_waitcnt lgkmcnt(4)
	v_cvt_pk_bf16_f32 v109, v134, v136
	v_pk_add_f32 v[66:67], v[66:67], v[68:69] neg_lo:[0,1] neg_hi:[0,1]
	v_mov_b32_e32 v68, v134
	v_mov_b32_e32 v69, v136
	v_lshlrev_b32_e32 v110, 16, v109
	v_and_b32_e32 v111, 0xffff0000, v109
	v_pk_add_f32 v[68:69], v[68:69], v[110:111] neg_lo:[0,1] neg_hi:[0,1]
	s_waitcnt lgkmcnt(2)
	v_cvt_pk_bf16_f32 v110, v138, v140
	v_cvt_pk_bf16_f32 v66, v66, v67
	v_cvt_pk_bf16_f32 v67, v68, v69
	v_mov_b32_e32 v68, v138
	v_mov_b32_e32 v69, v140
	v_lshlrev_b32_e32 v128, 16, v110
	v_and_b32_e32 v129, 0xffff0000, v110
	s_waitcnt lgkmcnt(0)
	v_cvt_pk_bf16_f32 v111, v142, v144
	v_pk_add_f32 v[68:69], v[68:69], v[128:129] neg_lo:[0,1] neg_hi:[0,1]
	v_mov_b32_e32 v128, v142
	v_mov_b32_e32 v129, v144
	v_lshlrev_b32_e32 v130, 16, v111
	v_and_b32_e32 v131, 0xffff0000, v111
	v_pk_add_f32 v[128:129], v[128:129], v[130:131] neg_lo:[0,1] neg_hi:[0,1]
	v_mfma_f32_16x16x32_bf16 v[54:57], v[74:77], v[108:111], v[54:57]
	v_cvt_pk_bf16_f32 v68, v68, v69
	v_cvt_pk_bf16_f32 v69, v128, v129
	v_mov_b32_e32 v82, v85
	v_mfma_f32_16x16x32_bf16 v[128:131], v[74:77], v[70:73], 0
	v_cvt_pk_bf16_f32 v84, v85, v83
	v_cvt_pk_bf16_f32 v85, v89, v87
	v_mov_b32_e32 v86, v89
	v_mfma_f32_16x16x32_bf16 v[54:57], v[58:61], v[66:69], v[54:57]
	v_mov_b32_e32 v96, v99
	v_mov_b32_e32 v100, v103
	v_mov_b32_e32 v104, v133
	v_mfma_f32_16x16x32_bf16 v[62:65], v[58:61], v[62:65], v[128:131]
	v_mov_b32_e32 v136, v135
	v_cvt_pk_bf16_f32 v98, v139, v141
	v_mov_b32_e32 v140, v139
	v_mfma_f32_16x16x32_bf16 v[66:69], v[58:61], v[108:111], v[54:57]
	v_mov_b32_e32 v144, v143
	s_nop 1
	v_mov_b32_e32 v54, v92
	v_mov_b32_e32 v55, v6
	v_mov_b32_e32 v56, v94
	v_mov_b32_e32 v57, v8
	v_mfma_f32_16x16x32_bf16 v[62:65], v[58:61], v[70:73], v[62:65]
	v_mov_b32_e32 v6, v93
	v_mov_b32_e32 v8, v95
	v_mfma_f32_16x16x32_bf16 v[54:57], v[78:81], v[70:73], v[54:57]
	v_lshlrev_b32_e32 v70, 16, v84
	v_and_b32_e32 v71, 0xffff0000, v84
	v_lshlrev_b32_e32 v72, 16, v85
	v_and_b32_e32 v73, 0xffff0000, v85
	v_pk_add_f32 v[70:71], v[82:83], v[70:71] neg_lo:[0,1] neg_hi:[0,1]
	v_pk_add_f32 v[72:73], v[86:87], v[72:73] neg_lo:[0,1] neg_hi:[0,1]
	v_cvt_pk_bf16_f32 v86, v99, v97
	v_cvt_pk_bf16_f32 v87, v103, v101
	v_cvt_pk_bf16_f32 v70, v70, v71
	v_cvt_pk_bf16_f32 v71, v72, v73
	v_lshlrev_b32_e32 v72, 16, v86
	v_and_b32_e32 v73, 0xffff0000, v86
	v_lshlrev_b32_e32 v82, 16, v87
	v_and_b32_e32 v83, 0xffff0000, v87
	v_pk_add_f32 v[72:73], v[96:97], v[72:73] neg_lo:[0,1] neg_hi:[0,1]
	v_pk_add_f32 v[82:83], v[100:101], v[82:83] neg_lo:[0,1] neg_hi:[0,1]
	v_cvt_pk_bf16_f32 v96, v133, v105
	v_cvt_pk_bf16_f32 v72, v72, v73
	v_cvt_pk_bf16_f32 v73, v82, v83
	v_lshlrev_b32_e32 v82, 16, v96
	v_and_b32_e32 v83, 0xffff0000, v96
	v_pk_add_f32 v[82:83], v[104:105], v[82:83] neg_lo:[0,1] neg_hi:[0,1]
	v_cvt_pk_bf16_f32 v97, v135, v137
	v_cvt_pk_bf16_f32 v100, v82, v83
	v_lshlrev_b32_e32 v82, 16, v97
	v_and_b32_e32 v83, 0xffff0000, v97
	v_pk_add_f32 v[82:83], v[136:137], v[82:83] neg_lo:[0,1] neg_hi:[0,1]
	v_cvt_pk_bf16_f32 v99, v143, v145
	v_cvt_pk_bf16_f32 v101, v82, v83
	v_lshlrev_b32_e32 v82, 16, v98
	v_and_b32_e32 v83, 0xffff0000, v98
	v_mfma_f32_16x16x32_bf16 v[50:53], v[78:81], v[108:111], v[50:53]
	v_add_f32_e64 v82, v140, -v82
	v_add_f32_e64 v83, v141, -v83
	v_cvt_pk_bf16_f32 v102, v82, v83
	v_mfma_f32_16x16x32_bf16 v[108:111], v[74:77], v[84:87], 0
	v_lshlrev_b32_e32 v82, 16, v99
	v_and_b32_e32 v83, 0xffff0000, v99
	v_pk_add_f32 v[82:83], v[144:145], v[82:83] neg_lo:[0,1] neg_hi:[0,1]
	v_mfma_f32_16x16x32_bf16 v[46:49], v[74:77], v[96:99], v[46:49]
	v_cvt_pk_bf16_f32 v103, v82, v83
	ds_read2_b32 v[82:83], v106 offset0:38 offset1:39
	v_mfma_f32_16x16x32_bf16 v[70:73], v[58:61], v[70:73], v[108:111]
	v_mfma_f32_16x16x32_bf16 v[46:49], v[58:61], v[100:103], v[46:49]
	v_mfma_f32_16x16x32_bf16 v[70:73], v[58:61], v[84:87], v[70:73]
	v_mfma_f32_16x16x32_bf16 v[46:49], v[58:61], v[96:99], v[46:49]
	v_add_u32_e32 v58, 0x6000, v126
	ds_read2_b32 v[60:61], v58 offset0:96 offset1:161
	v_add_u32_e32 v59, 0x6200, v126
	v_mfma_f32_16x16x32_bf16 v[6:9], v[78:81], v[84:87], v[6:9]
	s_waitcnt lgkmcnt(0)
	v_cvt_pk_bf16_f32 v58, v60, v61
	v_lshlrev_b32_e32 v74, 16, v58
	v_and_b32_e32 v75, 0xffff0000, v58
	v_pk_add_f32 v[60:61], v[60:61], v[74:75] neg_lo:[0,1] neg_hi:[0,1]
	v_mfma_f32_16x16x32_bf16 v[2:5], v[78:81], v[96:99], v[2:5]
	v_cvt_pk_bf16_f32 v74, v60, v61
	ds_read2_b32 v[60:61], v59 offset0:98 offset1:163
	s_waitcnt lgkmcnt(0)
	v_cvt_pk_bf16_f32 v59, v60, v61
	v_lshlrev_b32_e32 v76, 16, v59
	v_and_b32_e32 v77, 0xffff0000, v59
	v_pk_add_f32 v[60:61], v[60:61], v[76:77] neg_lo:[0,1] neg_hi:[0,1]
	s_nop 0
	v_cvt_pk_bf16_f32 v75, v60, v61
	v_add_u32_e32 v60, 0x6400, v126
	ds_read2_b32 v[76:77], v60 offset0:100 offset1:165
	v_add_u32_e32 v61, 0x6600, v126
	s_waitcnt lgkmcnt(0)
	v_cvt_pk_bf16_f32 v60, v76, v77
	v_lshlrev_b32_e32 v78, 16, v60
	v_and_b32_e32 v79, 0xffff0000, v60
	v_pk_add_f32 v[76:77], v[76:77], v[78:79] neg_lo:[0,1] neg_hi:[0,1]
	ds_read2_b32 v[78:79], v61 offset0:102 offset1:167
	v_cvt_pk_bf16_f32 v76, v76, v77
	s_waitcnt lgkmcnt(0)
	v_cvt_pk_bf16_f32 v61, v78, v79
	v_lshlrev_b32_e32 v80, 16, v61
	v_and_b32_e32 v81, 0xffff0000, v61
	v_pk_add_f32 v[78:79], v[78:79], v[80:81] neg_lo:[0,1] neg_hi:[0,1]
	ds_read2_b32 v[80:81], v106 offset0:34 offset1:35
	v_cvt_pk_bf16_f32 v77, v78, v79
	ds_read2_b32 v[78:79], v106 offset0:32 offset1:33
	s_waitcnt lgkmcnt(0)
	v_cvt_pk_bf16_f32 v78, v78, v79
	v_cvt_pk_bf16_f32 v79, v80, v81
	ds_read2_b32 v[80:81], v106 offset0:36 offset1:37
	s_waitcnt lgkmcnt(0)
	v_cvt_pk_bf16_f32 v80, v80, v81
	v_cvt_pk_bf16_f32 v81, v82, v83
	v_add_u32_e32 v83, 0x2000, v107
	ds_read2_b32 v[94:95], v83 offset0:32 offset1:48
	ds_read2_b32 v[92:93], v83 offset0:97 offset1:113
	ds_read2_b32 v[98:99], v83 offset0:162 offset1:178
	ds_read2_b32 v[96:97], v83 offset0:227 offset1:243
	s_waitcnt lgkmcnt(3)
	v_mov_b32_e32 v84, v94
	s_waitcnt lgkmcnt(2)
	v_cvt_pk_bf16_f32 v82, v94, v92
	v_mov_b32_e32 v85, v92
	v_lshlrev_b32_e32 v86, 16, v82
	v_and_b32_e32 v87, 0xffff0000, v82
	v_pk_add_f32 v[84:85], v[84:85], v[86:87] neg_lo:[0,1] neg_hi:[0,1]
	s_waitcnt lgkmcnt(0)
	v_cvt_pk_bf16_f32 v83, v98, v96
	v_cvt_pk_bf16_f32 v86, v84, v85
	v_mov_b32_e32 v84, v98
	v_mov_b32_e32 v85, v96
	v_lshlrev_b32_e32 v88, 16, v83
	v_and_b32_e32 v89, 0xffff0000, v83
	v_pk_add_f32 v[84:85], v[84:85], v[88:89] neg_lo:[0,1] neg_hi:[0,1]
	v_add_u32_e32 v92, 0x2000, v0
	v_cvt_pk_bf16_f32 v87, v84, v85
	v_add_u32_e32 v85, 0x2400, v107
	ds_read2_b32 v[102:103], v85 offset0:36 offset1:52
	ds_read2_b32 v[100:101], v85 offset0:101 offset1:117
	v_add_u32_e32 v0, 0x2400, v0
	v_mov_b32_e32 v96, v99
	s_waitcnt lgkmcnt(1)
	v_mov_b32_e32 v88, v102
	s_waitcnt lgkmcnt(0)
	v_cvt_pk_bf16_f32 v84, v102, v100
	v_mov_b32_e32 v89, v100
	v_lshlrev_b32_e32 v104, 16, v84
	v_and_b32_e32 v105, 0xffff0000, v84
	v_pk_add_f32 v[88:89], v[88:89], v[104:105] neg_lo:[0,1] neg_hi:[0,1]
	ds_read2_b32 v[106:107], v85 offset0:166 offset1:182
	ds_read2_b32 v[104:105], v85 offset0:231 offset1:247
	v_cvt_pk_bf16_f32 v88, v88, v89
	ds_read2_b32 v[130:131], v92 offset0:32 offset1:48
	ds_read2_b32 v[132:133], v92 offset0:97 offset1:113
	ds_read2_b32 v[134:135], v92 offset0:162 offset1:178
	ds_read2_b32 v[136:137], v92 offset0:227 offset1:243
	s_waitcnt lgkmcnt(5)
	v_mov_b32_e32 v108, v106
	s_waitcnt lgkmcnt(4)
	v_cvt_pk_bf16_f32 v85, v106, v104
	v_mov_b32_e32 v109, v104
	v_lshlrev_b32_e32 v110, 16, v85
	v_mfma_f32_16x16x32_bf16 v[62:65], v[74:77], v[82:85], v[62:65]
	v_and_b32_e32 v111, 0xffff0000, v85
	v_pk_add_f32 v[108:109], v[108:109], v[110:111] neg_lo:[0,1] neg_hi:[0,1]
	ds_read2_b32 v[138:139], v0 offset0:36 offset1:52
	ds_read2_b32 v[140:141], v0 offset0:101 offset1:117
	v_cvt_pk_bf16_f32 v89, v108, v109
	v_mfma_f32_16x16x32_bf16 v[54:57], v[78:81], v[82:85], v[54:57]
	s_waitcnt lgkmcnt(4)
	v_cvt_pk_bf16_f32 v108, v130, v132
	v_mov_b32_e32 v92, v95
	v_mov_b32_e32 v110, v130
	v_mfma_f32_16x16x32_bf16 v[62:65], v[58:61], v[86:89], v[62:65]
	v_mov_b32_e32 v111, v132
	v_lshlrev_b32_e32 v126, 16, v108
	v_and_b32_e32 v127, 0xffff0000, v108
	v_mfma_f32_16x16x32_bf16 v[62:65], v[58:61], v[82:85], v[62:65]
	v_cvt_pk_bf16_f32 v82, v95, v93
	v_lshlrev_b32_e32 v84, 16, v82
	v_and_b32_e32 v85, 0xffff0000, v82
	v_pk_add_f32 v[84:85], v[92:93], v[84:85] neg_lo:[0,1] neg_hi:[0,1]
	v_cvt_pk_bf16_f32 v83, v99, v97
	v_pk_add_f32 v[110:111], v[110:111], v[126:127] neg_lo:[0,1] neg_hi:[0,1]
	s_waitcnt lgkmcnt(2)
	v_cvt_pk_bf16_f32 v109, v134, v136
	v_cvt_pk_bf16_f32 v86, v84, v85
	v_lshlrev_b32_e32 v84, 16, v83
	v_and_b32_e32 v85, 0xffff0000, v83
	v_cvt_pk_bf16_f32 v126, v110, v111
	v_mov_b32_e32 v110, v134
	v_mov_b32_e32 v111, v136
	v_lshlrev_b32_e32 v128, 16, v109
	v_and_b32_e32 v129, 0xffff0000, v109
	v_pk_add_f32 v[84:85], v[96:97], v[84:85] neg_lo:[0,1] neg_hi:[0,1]
	v_pk_add_f32 v[110:111], v[110:111], v[128:129] neg_lo:[0,1] neg_hi:[0,1]
	v_cvt_pk_bf16_f32 v87, v84, v85
	v_cvt_pk_bf16_f32 v84, v103, v101
	v_cvt_pk_bf16_f32 v85, v107, v105
	v_cvt_pk_bf16_f32 v127, v110, v111
	s_waitcnt lgkmcnt(0)
	v_cvt_pk_bf16_f32 v110, v138, v140
	v_mov_b32_e32 v100, v103
	v_lshlrev_b32_e32 v88, 16, v84
	v_and_b32_e32 v89, 0xffff0000, v84
	v_mov_b32_e32 v104, v107
	v_lshlrev_b32_e32 v92, 16, v85
	v_and_b32_e32 v93, 0xffff0000, v85
	v_mov_b32_e32 v128, v138
	v_mov_b32_e32 v129, v140
	v_lshlrev_b32_e32 v142, 16, v110
	v_and_b32_e32 v143, 0xffff0000, v110
	v_pk_add_f32 v[88:89], v[100:101], v[88:89] neg_lo:[0,1] neg_hi:[0,1]
	v_pk_add_f32 v[92:93], v[104:105], v[92:93] neg_lo:[0,1] neg_hi:[0,1]
	v_pk_add_f32 v[128:129], v[128:129], v[142:143] neg_lo:[0,1] neg_hi:[0,1]
	ds_read2_b32 v[142:143], v0 offset0:166 offset1:182
	ds_read2_b32 v[144:145], v0 offset0:231 offset1:247
	v_cvt_pk_bf16_f32 v88, v88, v89
	v_cvt_pk_bf16_f32 v89, v92, v93
	v_cvt_pk_bf16_f32 v92, v131, v133
	v_mov_b32_e32 v132, v131
	v_lshlrev_b32_e32 v94, 16, v92
	v_and_b32_e32 v95, 0xffff0000, v92
	v_pk_add_f32 v[94:95], v[132:133], v[94:95] neg_lo:[0,1] neg_hi:[0,1]
	v_cvt_pk_bf16_f32 v93, v135, v137
	v_cvt_pk_bf16_f32 v96, v94, v95
	v_mov_b32_e32 v136, v135
	v_lshlrev_b32_e32 v94, 16, v93
	v_and_b32_e32 v95, 0xffff0000, v93
	v_pk_add_f32 v[94:95], v[136:137], v[94:95] neg_lo:[0,1] neg_hi:[0,1]
	s_waitcnt lgkmcnt(0)
	v_cvt_pk_bf16_f32 v111, v142, v144
	v_cvt_pk_bf16_f32 v97, v94, v95
	v_cvt_pk_bf16_f32 v94, v139, v141
	v_cvt_pk_bf16_f32 v95, v143, v145
	v_mfma_f32_16x16x32_bf16 v[66:69], v[74:77], v[108:111], v[66:69]
	v_mov_b32_e32 v146, v142
	v_mov_b32_e32 v147, v144
	v_lshlrev_b32_e32 v148, 16, v111
	v_mfma_f32_16x16x32_bf16 v[70:73], v[74:77], v[82:85], v[70:73]
	v_and_b32_e32 v149, 0xffff0000, v111
	v_mov_b32_e32 v140, v139
	v_lshlrev_b32_e32 v98, 16, v94
	v_mfma_f32_16x16x32_bf16 v[46:49], v[74:77], v[92:95], v[46:49]
	v_and_b32_e32 v99, 0xffff0000, v94
	v_mov_b32_e32 v144, v143
	v_lshlrev_b32_e32 v100, 16, v95
	v_and_b32_e32 v101, 0xffff0000, v95
	v_pk_add_f32 v[146:147], v[146:147], v[148:149] neg_lo:[0,1] neg_hi:[0,1]
	v_pk_add_f32 v[98:99], v[140:141], v[98:99] neg_lo:[0,1] neg_hi:[0,1]
	v_pk_add_f32 v[100:101], v[144:145], v[100:101] neg_lo:[0,1] neg_hi:[0,1]
	v_cvt_pk_bf16_f32 v128, v128, v129
	v_cvt_pk_bf16_f32 v129, v146, v147
	v_cvt_pk_bf16_f32 v98, v98, v99
	v_cvt_pk_bf16_f32 v99, v100, v101
	v_mfma_f32_16x16x32_bf16 v[66:69], v[58:61], v[126:129], v[66:69]
	v_lshl_add_u32 v0, v124, 2, v116
	v_mfma_f32_16x16x32_bf16 v[70:73], v[58:61], v[86:89], v[70:73]
	v_mfma_f32_16x16x32_bf16 v[46:49], v[58:61], v[96:99], v[46:49]
	v_mfma_f32_16x16x32_bf16 v[66:69], v[58:61], v[108:111], v[66:69]
	v_mfma_f32_16x16x32_bf16 v[70:73], v[58:61], v[82:85], v[70:73]
	v_mfma_f32_16x16x32_bf16 v[46:49], v[58:61], v[92:95], v[46:49]
	ds_read_b128 v[58:61], v0
	v_cndmask_b32_e64 v0, 0, 1.0, vcc
	v_add_f32_e32 v0, v0, v62
	v_mfma_f32_16x16x32_bf16 v[50:53], v[78:81], v[108:111], v[50:53]
	v_cmp_eq_u32_e32 vcc, v125, v120
	s_waitcnt lgkmcnt(0)
	v_mul_f32_e32 v0, v0, v58
	s_nop 0
	v_mul_f32_e32 v46, v46, v58
	v_mfma_f32_16x16x32_bf16 v[6:9], v[78:81], v[82:85], v[6:9]
	v_mfma_f32_16x16x32_bf16 v[2:5], v[78:81], v[92:95], v[2:5]
	v_lshlrev_b32_e32 v81, 6, v124
	v_or_b32_e32 v74, v81, v120
	v_ashrrev_i32_e32 v75, 31, v74
	v_or_b32_e32 v80, 0x1000, v120
	v_lshl_add_u64 v[76:77], v[74:75], 2, s[82:83]
	global_store_dword v[76:77], v0, off
	v_add_u32_e32 v76, v81, v80
	v_ashrrev_i32_e32 v77, 31, v76
	v_mul_f32_e32 v0, v66, v58
	v_lshl_add_u64 v[78:79], v[76:77], 2, s[82:83]
	global_store_dword v[78:79], v0, off
	v_cvt_pk_bf16_f32 v0, v54, s0
	v_lshl_add_u64 v[78:79], v[74:75], 1, s[2:3]
	global_store_short v[78:79], v0, off
	v_cvt_pk_bf16_f32 v0, v50, s0
	v_lshl_add_u64 v[76:77], v[76:77], 1, s[2:3]
	v_lshlrev_b32_e32 v78, 6, v125
	global_store_short v[76:77], v0, off
	v_cndmask_b32_e64 v0, 0, 1.0, vcc
	v_or_b32_e32 v62, v78, v120
	v_add_f32_e32 v0, v0, v63
	v_ashrrev_i32_e32 v63, 31, v62
	v_mul_f32_e32 v0, v0, v59
	v_lshl_add_u64 v[76:77], v[62:63], 2, s[82:83]
	v_add_u32_e32 v66, v78, v80
	global_store_dword v[76:77], v0, off
	v_mul_f32_e32 v0, v67, v59
	v_ashrrev_i32_e32 v67, 31, v66
	v_lshl_add_u64 v[76:77], v[66:67], 2, s[82:83]
	global_store_dword v[76:77], v0, off
	v_cvt_pk_bf16_f32 v0, v55, s0
	v_lshl_add_u64 v[54:55], v[62:63], 1, s[2:3]
	global_store_short v[54:55], v0, off
	v_cvt_pk_bf16_f32 v0, v51, s0
	v_lshl_add_u64 v[50:51], v[66:67], 1, s[2:3]
	v_cmp_eq_u32_e32 vcc, v123, v120
	v_lshlrev_b32_e32 v76, 6, v123
	global_store_short v[50:51], v0, off
	v_cndmask_b32_e64 v0, 0, 1.0, vcc
	v_or_b32_e32 v50, v76, v120
	v_add_f32_e32 v0, v0, v64
	v_ashrrev_i32_e32 v51, 31, v50
	v_mul_f32_e32 v0, v0, v60
	v_lshl_add_u64 v[54:55], v[50:51], 2, s[82:83]
	global_store_dword v[54:55], v0, off
	v_add_u32_e32 v54, v76, v80
	v_ashrrev_i32_e32 v55, 31, v54
	v_mul_f32_e32 v0, v68, v60
	v_lshl_add_u64 v[66:67], v[54:55], 2, s[82:83]
	global_store_dword v[66:67], v0, off
	v_cvt_pk_bf16_f32 v0, v56, s0
	v_lshl_add_u64 v[66:67], v[50:51], 1, s[2:3]
	global_store_short v[66:67], v0, off
	v_cvt_pk_bf16_f32 v0, v52, s0
	v_lshl_add_u64 v[54:55], v[54:55], 1, s[2:3]
	v_cmp_eq_u32_e32 vcc, v121, v120
	v_lshlrev_b32_e32 v68, 6, v121
	global_store_short v[54:55], v0, off
	v_cndmask_b32_e64 v0, 0, 1.0, vcc
	v_or_b32_e32 v54, v68, v120
	v_add_f32_e32 v0, v0, v65
	v_ashrrev_i32_e32 v55, 31, v54
	v_mul_f32_e32 v0, v0, v61
	v_lshl_add_u64 v[64:65], v[54:55], 2, s[82:83]
	global_store_dword v[64:65], v0, off
	v_add_u32_e32 v64, v68, v80
	v_ashrrev_i32_e32 v65, 31, v64
	v_mul_f32_e32 v0, v69, v61
	v_lshl_add_u64 v[66:67], v[64:65], 2, s[82:83]
	v_cmp_eq_u32_e32 vcc, v124, v122
	global_store_dword v[66:67], v0, off
	v_cvt_pk_bf16_f32 v0, v57, s0
	v_lshl_add_u64 v[56:57], v[54:55], 1, s[2:3]
	v_cndmask_b32_e64 v51, 0, 1.0, vcc
	global_store_short v[56:57], v0, off
	v_cvt_pk_bf16_f32 v0, v53, s0
	v_lshl_add_u64 v[52:53], v[64:65], 1, s[2:3]
	v_add_f32_e32 v51, v51, v70
	v_ashrrev_i32_e32 v75, 31, v81
	global_store_short v[52:53], v0, off
	v_or_b32_e32 v0, 0x1010, v120
	v_mul_f32_e32 v51, v51, v58
	v_lshl_add_u64 v[52:53], v[74:75], 2, s[82:83]
	global_store_dword v[52:53], v51, off offset:64
	v_add_u32_e32 v52, v81, v0
	v_ashrrev_i32_e32 v53, 31, v52
	v_lshl_add_u64 v[56:57], v[52:53], 2, s[82:83]
	global_store_dword v[56:57], v46, off
	v_cvt_pk_bf16_f32 v6, v6, s0
	v_lshl_add_u64 v[56:57], v[74:75], 1, s[2:3]
	v_cvt_pk_bf16_f32 v2, v2, s0
	v_lshl_add_u64 v[52:53], v[52:53], 1, s[2:3]
	v_cmp_eq_u32_e32 vcc, v125, v122
	global_store_short v[56:57], v6, off offset:32
	global_store_short v[52:53], v2, off
	v_cndmask_b32_e64 v2, 0, 1.0, vcc
	v_add_f32_e32 v2, v2, v71
	v_ashrrev_i32_e32 v63, 31, v78
	v_mul_f32_e32 v2, v2, v59
	v_lshl_add_u64 v[52:53], v[62:63], 2, s[82:83]
	v_add_u32_e32 v46, v78, v0
	global_store_dword v[52:53], v2, off offset:64
	v_mul_f32_e32 v2, v47, v59
	v_ashrrev_i32_e32 v47, 31, v46
	v_lshl_add_u64 v[52:53], v[46:47], 2, s[82:83]
	global_store_dword v[52:53], v2, off
	v_cvt_pk_bf16_f32 v2, v7, s0
	v_lshl_add_u64 v[6:7], v[62:63], 1, s[2:3]
	global_store_short v[6:7], v2, off offset:32
	v_cvt_pk_bf16_f32 v6, v3, s0
	v_lshl_add_u64 v[2:3], v[46:47], 1, s[2:3]
	v_cmp_eq_u32_e32 vcc, v123, v122
	global_store_short v[2:3], v6, off
	v_ashrrev_i32_e32 v51, 31, v76
	v_cndmask_b32_e64 v2, 0, 1.0, vcc
	v_add_f32_e32 v2, v2, v72
	v_mul_f32_e32 v6, v2, v60
	v_lshl_add_u64 v[2:3], v[50:51], 2, s[82:83]
	global_store_dword v[2:3], v6, off offset:64
	v_add_u32_e32 v2, v76, v0
	v_ashrrev_i32_e32 v3, 31, v2
	v_mul_f32_e32 v46, v48, v60
	v_lshl_add_u64 v[6:7], v[2:3], 2, s[82:83]
	global_store_dword v[6:7], v46, off
	v_cvt_pk_bf16_f32 v8, v8, s0
	v_lshl_add_u64 v[6:7], v[50:51], 1, s[2:3]
	v_cvt_pk_bf16_f32 v4, v4, s0
	v_lshl_add_u64 v[2:3], v[2:3], 1, s[2:3]
	v_cmp_eq_u32_e32 vcc, v121, v122
	global_store_short v[6:7], v8, off offset:32
	global_store_short v[2:3], v4, off
	v_cndmask_b32_e64 v2, 0, 1.0, vcc
	v_add_f32_e32 v2, v2, v73
	v_ashrrev_i32_e32 v55, 31, v68
	v_mul_f32_e32 v4, v2, v61
	v_lshl_add_u64 v[2:3], v[54:55], 2, s[82:83]
	global_store_dword v[2:3], v4, off offset:64
	v_add_u32_e32 v2, v68, v0
	v_ashrrev_i32_e32 v3, 31, v2
	v_mul_f32_e32 v4, v49, v61
	v_lshl_add_u64 v[6:7], v[2:3], 2, s[82:83]
	global_store_dword v[6:7], v4, off
	v_cvt_pk_bf16_f32 v0, v9, s0
	v_lshl_add_u64 v[6:7], v[54:55], 1, s[2:3]
	global_store_short v[6:7], v0, off offset:32
	v_cvt_pk_bf16_f32 v0, v5, s0
	v_lshl_add_u64 v[2:3], v[2:3], 1, s[2:3]
	global_store_short v[2:3], v0, off
	s_waitcnt vmcnt(32)
	s_barrier
